# v15: v13 plus no grid barrier between the W1 and W2 compress GEMMs (each W2 tile consumes exactly the W1 tile its own workgroup produced; local vmcnt(0)+L1 invalidate+s_barrier instead)
# speedup vs baseline: 1.0052x; 1.0052x over previous
; DI unsigned xb_add(unsigned* p, unsigned v) { return __hip_atomic_fetch_add(p, v, __ATOMIC_RELAXED, __HIP_MEMORY_SCOPE_AGENT); }
; DI void xcd_barrier(const XcdBarrier& b) {
;   asm volatile("s_waitcnt vmcnt(0)" ::: "memory");
;   __syncthreads();
;   if (threadIdx.x == 0) {
;     unsigned* bar = b.bar;
;     __builtin_amdgcn_s_waitcnt(0);
;     unsigned nloc = b.st[0], nx = b.st[1];
;     if (nloc == 0u) { xcd_barrier_complete(bar, b.x, nloc, nx); b.st[0] = nloc; b.st[1] = nx; }
;     const unsigned old = xb_add(&bar[XB_XSUB(b.x)], 1u);
; __global__ void __launch_bounds__(256, 2) mega(Params p) {
;     ...
;       xcd_barrier(xb);
;       ga = GArgs{}; ga.A = hck; ga.lda = 128; ga.Bt = (bf16_t*)(ws + W_W2) + (size_t)(j * 2) * 128 * 128; ga.K = 128; ga.M = 2048; ga.Npad = 128; ga.C = kcmp; ga.ldc = 128;
;       gemm_phase<EPI_BF16>(ga, smem);
.LBB0_367:
	s_waitcnt vmcnt(0)
	s_waitcnt vmcnt(0) lgkmcnt(0)
	buffer_inv sc1
	s_waitcnt vmcnt(0)
	s_barrier
	s_mov_b64 s[0:1], exec
	v_readlane_b32 s2, v250, 0
	v_readlane_b32 s3, v250, 1
	s_and_b64 s[2:3], s[0:1], s[2:3]
	s_mov_b64 exec, s[2:3]
	s_branch .LBB0_415
	s_waitcnt vmcnt(0) expcnt(0) lgkmcnt(0)
	ds_read_b32 v3, v192
	ds_read_b32 v2, v193
	s_waitcnt lgkmcnt(1)
	v_cmp_ne_u32_e32 vcc, 0, v3
	s_cbranch_vccnz .LBB0_383
	s_mov_b32 s8, 1
	s_branch .LBB0_371
